# instruction-count reduction: two-address LDS reads/writes (ds_read2/ds_write2) for the state, v_new and substitution column fragments
# speedup vs baseline: 1.0047x; 1.0047x over previous
; __device__ __forceinline__ void dn_task(const Params& p, int l, int task, char* smem) {
;     ...
;     {
;       const int did = tid >> 2, pp = did >> 2, wh = did & 3, part = tid & 3;
;       const float* xr = (wh == 0) ? (ks + (2 * pp + 1) * 68) : (wh == 1) ? (qs + (2 * pp) * 68) : (qs + (2 * pp + 1) * 68);
;       const float* yr = (wh == 3) ? (ks + (2 * pp + 1) * 68) : (ks + (2 * pp) * 68);
;       float sdot = 0.f;
; #pragma unroll
;       for (int i = 0; i < 16; ++i) sdot += xr[part * 16 + i] * yr[part * 16 + i];
;       sdot = quad_sum(sdot);
;       if (part == 0) dots[did] = sdot;
;     }
.LBB0_207:
	s_waitcnt lgkmcnt(0)
	s_barrier
	v_and_b32_e32 v221, 63, v172
	v_and_b32_e32 v222, 15, v221
	v_lshrrev_b32_e32 v223, 4, v221
	v_mul_u32_u24_e32 v224, 0x110, v222
	v_lshl_add_u32 v224, v223, 6, v224
	v_mul_u32_u24_e32 v225, 0x240, v223
	v_lshl_add_u32 v225, v222, 2, v225
	v_readfirstlane_b32 s60, v172
	s_nop 3
	s_lshr_b32 s60, s60, 6
	v_lshrrev_b32_e32 v244, 3, v172
	v_lshlrev_b32_e32 v244, 2, v244
	v_sub_u32_e32 v248, v167, v244
	s_and_b32 s61, s60, 1
	s_lshl_b32 s61, s61, 6
	v_mul_u32_u24_e32 v244, 0x840, v223
	v_lshl_add_u32 v244, v222, 2, v244
	s_add_i32 s61, s61, 0x11600
	v_add_u32_e32 v244, s61, v244
	v_add_u32_e32 v245, 0x420, v244
	ds_read2_b32 v[10:11], v244 offset0:0 offset1:33
	ds_read2_b32 v[12:13], v244 offset0:66 offset1:99
	ds_read2_b32 v[14:15], v244 offset0:132 offset1:165
	ds_read2_b32 v[16:17], v244 offset0:198 offset1:231
	ds_read2_b32 v[18:19], v245 offset0:0 offset1:33
	ds_read2_b32 v[20:21], v245 offset0:66 offset1:99
	ds_read2_b32 v[22:23], v245 offset0:132 offset1:165
	ds_read2_b32 v[24:25], v245 offset0:198 offset1:231
	s_lshr_b32 s61, s60, 1
	s_mul_i32 s70, s61, 0x1100
	v_add_u32_e32 v246, s70, v224
	ds_read_b128 v[66:69], v246 offset:8704
	ds_read_b128 v[70:73], v246 offset:8720
	ds_read_b128 v[74:77], v246 offset:8736
	ds_read_b128 v[78:81], v246 offset:8752
	s_cmp_eq_u32 s60, 3
	s_cbranch_scc1 .Ldc_w3
	s_cmp_eq_u32 s60, 1
	s_cbranch_scc1 .Ldc_k1
	s_waitcnt lgkmcnt(0)
	v_mfma_f32_16x16x4_f32 v[62:65], v66, v10, 0
	v_mfma_f32_16x16x4_f32 v[58:61], v66, v66, 0
	v_mfma_f32_16x16x4_f32 v[62:65], v67, v11, v[62:65]
	v_mfma_f32_16x16x4_f32 v[58:61], v67, v67, v[58:61]
	v_mfma_f32_16x16x4_f32 v[62:65], v68, v12, v[62:65]
	v_mfma_f32_16x16x4_f32 v[58:61], v68, v68, v[58:61]
	v_mfma_f32_16x16x4_f32 v[62:65], v69, v13, v[62:65]
	v_mfma_f32_16x16x4_f32 v[58:61], v69, v69, v[58:61]
	v_mfma_f32_16x16x4_f32 v[62:65], v70, v14, v[62:65]
	v_mfma_f32_16x16x4_f32 v[58:61], v70, v70, v[58:61]
	v_mfma_f32_16x16x4_f32 v[62:65], v71, v15, v[62:65]
	v_mfma_f32_16x16x4_f32 v[58:61], v71, v71, v[58:61]
	v_mfma_f32_16x16x4_f32 v[62:65], v72, v16, v[62:65]
	v_mfma_f32_16x16x4_f32 v[58:61], v72, v72, v[58:61]
	v_mfma_f32_16x16x4_f32 v[62:65], v73, v17, v[62:65]
	v_mfma_f32_16x16x4_f32 v[58:61], v73, v73, v[58:61]
	v_mfma_f32_16x16x4_f32 v[62:65], v74, v18, v[62:65]
	v_mfma_f32_16x16x4_f32 v[58:61], v74, v74, v[58:61]
	v_mfma_f32_16x16x4_f32 v[62:65], v75, v19, v[62:65]
	v_mfma_f32_16x16x4_f32 v[58:61], v75, v75, v[58:61]
	v_mfma_f32_16x16x4_f32 v[62:65], v76, v20, v[62:65]
	v_mfma_f32_16x16x4_f32 v[58:61], v76, v76, v[58:61]
	v_mfma_f32_16x16x4_f32 v[62:65], v77, v21, v[62:65]
	v_mfma_f32_16x16x4_f32 v[58:61], v77, v77, v[58:61]
	v_mfma_f32_16x16x4_f32 v[62:65], v78, v22, v[62:65]
	v_mfma_f32_16x16x4_f32 v[58:61], v78, v78, v[58:61]
	v_mfma_f32_16x16x4_f32 v[62:65], v79, v23, v[62:65]
	v_mfma_f32_16x16x4_f32 v[58:61], v79, v79, v[58:61]
	v_mfma_f32_16x16x4_f32 v[62:65], v80, v24, v[62:65]
	v_mfma_f32_16x16x4_f32 v[58:61], v80, v80, v[58:61]
	v_mfma_f32_16x16x4_f32 v[62:65], v81, v25, v[62:65]
	v_mfma_f32_16x16x4_f32 v[58:61], v81, v81, v[58:61]
	s_branch .Ldc_b1

.Ldc_b2:
	s_waitcnt lgkmcnt(0)
	s_barrier
	s_cmp_ge_u32 s60, 2
	s_cbranch_scc1 .Ldc_s2q
	s_cmp_eq_u32 s60, 1
	s_cbranch_scc1 .Ldc_s2k
	s_mov_b32 exec_hi, 0
	v_and_b32_e32 v135, 31, v221
	v_lshlrev_b32_e32 v135, 2, v135
	v_add_u32_e32 v135, 0xe200, v135
	v_add_u32_e32 v245, 0x480, v135
	v_add_u32_e32 v246, 0x900, v135
	v_add_u32_e32 v247, 0xd80, v135
	ds_read2_b32 v[10:11], v135 offset0:0 offset1:36
	ds_read2_b32 v[12:13], v135 offset0:72 offset1:108
	ds_read2_b32 v[14:15], v135 offset0:144 offset1:180
	ds_read2_b32 v[16:17], v135 offset0:216 offset1:252
	ds_read2_b32 v[18:19], v245 offset0:0 offset1:36
	ds_read2_b32 v[20:21], v245 offset0:72 offset1:108
	ds_read2_b32 v[22:23], v245 offset0:144 offset1:180
	ds_read2_b32 v[24:25], v245 offset0:216 offset1:252
	ds_read2_b32 v[26:27], v246 offset0:0 offset1:36
	ds_read2_b32 v[28:29], v246 offset0:72 offset1:108
	ds_read2_b32 v[30:31], v246 offset0:144 offset1:180
	ds_read2_b32 v[32:33], v246 offset0:216 offset1:252
	ds_read2_b32 v[34:35], v247 offset0:0 offset1:36
	ds_read2_b32 v[36:37], v247 offset0:72 offset1:108
	ds_read2_b32 v[38:39], v247 offset0:144 offset1:180
	ds_read2_b32 v[40:41], v247 offset0:216 offset1:252
	ds_read_b128 v[42:45], v1 offset:44032
	ds_read_b128 v[46:49], v1 offset:44048
	ds_read_b128 v[50:53], v1 offset:44064
	ds_read_b128 v[54:57], v1 offset:44080
	ds_read_b128 v[58:61], v1 offset:44096
	ds_read_b128 v[62:65], v1 offset:44112
	ds_read_b128 v[66:69], v1 offset:44128
	ds_read_b128 v[70:73], v1 offset:44144
	ds_read_b128 v[74:77], v1 offset:44176
	ds_read_b128 v[78:81], v1 offset:44192
	ds_read_b128 v[82:85], v1 offset:44208
	ds_read_b128 v[86:89], v1 offset:44224
	ds_read_b128 v[226:229], v1 offset:44240
	ds_read_b128 v[230:233], v1 offset:44256
	ds_read_b128 v[234:237], v1 offset:44272
	ds_read_b128 v[238:241], v1 offset:44288
	s_waitcnt lgkmcnt(0)
	v_fmac_f32_e32 v11, v43, v10
	v_pk_fma_f32 v[12:13], v[44:45], v[10:11], v[12:13] op_sel:[0,0,0] op_sel_hi:[1,0,1]
	v_pk_fma_f32 v[14:15], v[46:47], v[10:11], v[14:15] op_sel:[0,0,0] op_sel_hi:[1,0,1]
	v_pk_fma_f32 v[16:17], v[48:49], v[10:11], v[16:17] op_sel:[0,0,0] op_sel_hi:[1,0,1]
	v_pk_fma_f32 v[18:19], v[50:51], v[10:11], v[18:19] op_sel:[0,0,0] op_sel_hi:[1,0,1]
	v_pk_fma_f32 v[20:21], v[52:53], v[10:11], v[20:21] op_sel:[0,0,0] op_sel_hi:[1,0,1]
	v_pk_fma_f32 v[22:23], v[54:55], v[10:11], v[22:23] op_sel:[0,0,0] op_sel_hi:[1,0,1]
	v_pk_fma_f32 v[24:25], v[56:57], v[10:11], v[24:25] op_sel:[0,0,0] op_sel_hi:[1,0,1]
	v_pk_fma_f32 v[26:27], v[58:59], v[10:11], v[26:27] op_sel:[0,0,0] op_sel_hi:[1,0,1]
	v_pk_fma_f32 v[28:29], v[60:61], v[10:11], v[28:29] op_sel:[0,0,0] op_sel_hi:[1,0,1]
	v_pk_fma_f32 v[30:31], v[62:63], v[10:11], v[30:31] op_sel:[0,0,0] op_sel_hi:[1,0,1]
	v_pk_fma_f32 v[32:33], v[64:65], v[10:11], v[32:33] op_sel:[0,0,0] op_sel_hi:[1,0,1]
	v_pk_fma_f32 v[34:35], v[66:67], v[10:11], v[34:35] op_sel:[0,0,0] op_sel_hi:[1,0,1]
	v_pk_fma_f32 v[36:37], v[68:69], v[10:11], v[36:37] op_sel:[0,0,0] op_sel_hi:[1,0,1]
	v_pk_fma_f32 v[38:39], v[70:71], v[10:11], v[38:39] op_sel:[0,0,0] op_sel_hi:[1,0,1]
	v_pk_fma_f32 v[40:41], v[72:73], v[10:11], v[40:41] op_sel:[0,0,0] op_sel_hi:[1,0,1]
	ds_read_b128 v[42:45], v1 offset:44320
	ds_read_b128 v[46:49], v1 offset:44336
	ds_read_b128 v[50:53], v1 offset:44352
	ds_read_b128 v[54:57], v1 offset:44368
	ds_read_b128 v[58:61], v1 offset:44384
	ds_read_b128 v[62:65], v1 offset:44400
	ds_read_b128 v[66:69], v1 offset:44416
	ds_read_b128 v[70:73], v1 offset:44432
	s_waitcnt lgkmcnt(0)
	v_pk_fma_f32 v[12:13], v[76:77], v[10:11], v[12:13] op_sel:[0,1,0] op_sel_hi:[1,1,1]
	v_pk_fma_f32 v[14:15], v[78:79], v[10:11], v[14:15] op_sel:[0,1,0] op_sel_hi:[1,1,1]
	v_pk_fma_f32 v[16:17], v[80:81], v[10:11], v[16:17] op_sel:[0,1,0] op_sel_hi:[1,1,1]
	v_pk_fma_f32 v[18:19], v[82:83], v[10:11], v[18:19] op_sel:[0,1,0] op_sel_hi:[1,1,1]
	v_pk_fma_f32 v[20:21], v[84:85], v[10:11], v[20:21] op_sel:[0,1,0] op_sel_hi:[1,1,1]
	v_pk_fma_f32 v[22:23], v[86:87], v[10:11], v[22:23] op_sel:[0,1,0] op_sel_hi:[1,1,1]
	v_pk_fma_f32 v[24:25], v[88:89], v[10:11], v[24:25] op_sel:[0,1,0] op_sel_hi:[1,1,1]
	v_pk_fma_f32 v[26:27], v[226:227], v[10:11], v[26:27] op_sel:[0,1,0] op_sel_hi:[1,1,1]
	v_pk_fma_f32 v[28:29], v[228:229], v[10:11], v[28:29] op_sel:[0,1,0] op_sel_hi:[1,1,1]
	v_pk_fma_f32 v[30:31], v[230:231], v[10:11], v[30:31] op_sel:[0,1,0] op_sel_hi:[1,1,1]
	v_pk_fma_f32 v[32:33], v[232:233], v[10:11], v[32:33] op_sel:[0,1,0] op_sel_hi:[1,1,1]
	v_pk_fma_f32 v[34:35], v[234:235], v[10:11], v[34:35] op_sel:[0,1,0] op_sel_hi:[1,1,1]
	v_pk_fma_f32 v[36:37], v[236:237], v[10:11], v[36:37] op_sel:[0,1,0] op_sel_hi:[1,1,1]
	v_pk_fma_f32 v[38:39], v[238:239], v[10:11], v[38:39] op_sel:[0,1,0] op_sel_hi:[1,1,1]
	v_pk_fma_f32 v[40:41], v[240:241], v[10:11], v[40:41] op_sel:[0,1,0] op_sel_hi:[1,1,1]
	ds_read_b128 v[78:81], v1 offset:44480
	ds_read_b128 v[82:85], v1 offset:44496
	ds_read_b128 v[86:89], v1 offset:44512
	ds_read_b128 v[226:229], v1 offset:44528
	ds_read_b128 v[230:233], v1 offset:44544
	ds_read_b128 v[234:237], v1 offset:44560
	ds_read_b128 v[238:241], v1 offset:44576
	s_waitcnt lgkmcnt(0)
	v_fmac_f32_e32 v13, v45, v12
	v_pk_fma_f32 v[14:15], v[46:47], v[12:13], v[14:15] op_sel:[0,0,0] op_sel_hi:[1,0,1]
	v_pk_fma_f32 v[16:17], v[48:49], v[12:13], v[16:17] op_sel:[0,0,0] op_sel_hi:[1,0,1]
	v_pk_fma_f32 v[18:19], v[50:51], v[12:13], v[18:19] op_sel:[0,0,0] op_sel_hi:[1,0,1]
	v_pk_fma_f32 v[20:21], v[52:53], v[12:13], v[20:21] op_sel:[0,0,0] op_sel_hi:[1,0,1]
	v_pk_fma_f32 v[22:23], v[54:55], v[12:13], v[22:23] op_sel:[0,0,0] op_sel_hi:[1,0,1]
	v_pk_fma_f32 v[24:25], v[56:57], v[12:13], v[24:25] op_sel:[0,0,0] op_sel_hi:[1,0,1]
	v_pk_fma_f32 v[26:27], v[58:59], v[12:13], v[26:27] op_sel:[0,0,0] op_sel_hi:[1,0,1]
	v_pk_fma_f32 v[28:29], v[60:61], v[12:13], v[28:29] op_sel:[0,0,0] op_sel_hi:[1,0,1]
	v_pk_fma_f32 v[30:31], v[62:63], v[12:13], v[30:31] op_sel:[0,0,0] op_sel_hi:[1,0,1]
	v_pk_fma_f32 v[32:33], v[64:65], v[12:13], v[32:33] op_sel:[0,0,0] op_sel_hi:[1,0,1]
	v_pk_fma_f32 v[34:35], v[66:67], v[12:13], v[34:35] op_sel:[0,0,0] op_sel_hi:[1,0,1]
	v_pk_fma_f32 v[36:37], v[68:69], v[12:13], v[36:37] op_sel:[0,0,0] op_sel_hi:[1,0,1]
	v_pk_fma_f32 v[38:39], v[70:71], v[12:13], v[38:39] op_sel:[0,0,0] op_sel_hi:[1,0,1]
	v_pk_fma_f32 v[40:41], v[72:73], v[12:13], v[40:41] op_sel:[0,0,0] op_sel_hi:[1,0,1]
	ds_read_b128 v[46:49], v1 offset:44624
	ds_read_b128 v[50:53], v1 offset:44640
	ds_read_b128 v[54:57], v1 offset:44656
	ds_read_b128 v[58:61], v1 offset:44672
	ds_read_b128 v[62:65], v1 offset:44688
	ds_read_b128 v[66:69], v1 offset:44704
	ds_read_b128 v[70:73], v1 offset:44720
	s_waitcnt lgkmcnt(0)
	v_pk_fma_f32 v[14:15], v[78:79], v[12:13], v[14:15] op_sel:[0,1,0] op_sel_hi:[1,1,1]
	v_pk_fma_f32 v[16:17], v[80:81], v[12:13], v[16:17] op_sel:[0,1,0] op_sel_hi:[1,1,1]
	v_pk_fma_f32 v[18:19], v[82:83], v[12:13], v[18:19] op_sel:[0,1,0] op_sel_hi:[1,1,1]
	v_pk_fma_f32 v[20:21], v[84:85], v[12:13], v[20:21] op_sel:[0,1,0] op_sel_hi:[1,1,1]
	v_pk_fma_f32 v[22:23], v[86:87], v[12:13], v[22:23] op_sel:[0,1,0] op_sel_hi:[1,1,1]
	v_pk_fma_f32 v[24:25], v[88:89], v[12:13], v[24:25] op_sel:[0,1,0] op_sel_hi:[1,1,1]
	v_pk_fma_f32 v[26:27], v[226:227], v[12:13], v[26:27] op_sel:[0,1,0] op_sel_hi:[1,1,1]
	v_pk_fma_f32 v[28:29], v[228:229], v[12:13], v[28:29] op_sel:[0,1,0] op_sel_hi:[1,1,1]
	v_pk_fma_f32 v[30:31], v[230:231], v[12:13], v[30:31] op_sel:[0,1,0] op_sel_hi:[1,1,1]
	v_pk_fma_f32 v[32:33], v[232:233], v[12:13], v[32:33] op_sel:[0,1,0] op_sel_hi:[1,1,1]
	v_pk_fma_f32 v[34:35], v[234:235], v[12:13], v[34:35] op_sel:[0,1,0] op_sel_hi:[1,1,1]
	v_pk_fma_f32 v[36:37], v[236:237], v[12:13], v[36:37] op_sel:[0,1,0] op_sel_hi:[1,1,1]
	v_pk_fma_f32 v[38:39], v[238:239], v[12:13], v[38:39] op_sel:[0,1,0] op_sel_hi:[1,1,1]
	v_pk_fma_f32 v[40:41], v[240:241], v[12:13], v[40:41] op_sel:[0,1,0] op_sel_hi:[1,1,1]
	ds_read_b128 v[78:81], v1 offset:44768
	ds_read_b128 v[82:85], v1 offset:44784
	ds_read_b128 v[86:89], v1 offset:44800
	ds_read_b128 v[226:229], v1 offset:44816
	ds_read_b128 v[230:233], v1 offset:44832
	ds_read_b128 v[234:237], v1 offset:44848
	ds_read_b128 v[238:241], v1 offset:44864
	s_waitcnt lgkmcnt(0)
	v_fmac_f32_e32 v15, v47, v14
	v_pk_fma_f32 v[16:17], v[48:49], v[14:15], v[16:17] op_sel:[0,0,0] op_sel_hi:[1,0,1]
	v_pk_fma_f32 v[18:19], v[50:51], v[14:15], v[18:19] op_sel:[0,0,0] op_sel_hi:[1,0,1]
	v_pk_fma_f32 v[20:21], v[52:53], v[14:15], v[20:21] op_sel:[0,0,0] op_sel_hi:[1,0,1]
	v_pk_fma_f32 v[22:23], v[54:55], v[14:15], v[22:23] op_sel:[0,0,0] op_sel_hi:[1,0,1]
	v_pk_fma_f32 v[24:25], v[56:57], v[14:15], v[24:25] op_sel:[0,0,0] op_sel_hi:[1,0,1]
	v_pk_fma_f32 v[26:27], v[58:59], v[14:15], v[26:27] op_sel:[0,0,0] op_sel_hi:[1,0,1]
	v_pk_fma_f32 v[28:29], v[60:61], v[14:15], v[28:29] op_sel:[0,0,0] op_sel_hi:[1,0,1]
	v_pk_fma_f32 v[30:31], v[62:63], v[14:15], v[30:31] op_sel:[0,0,0] op_sel_hi:[1,0,1]
	v_pk_fma_f32 v[32:33], v[64:65], v[14:15], v[32:33] op_sel:[0,0,0] op_sel_hi:[1,0,1]
	v_pk_fma_f32 v[34:35], v[66:67], v[14:15], v[34:35] op_sel:[0,0,0] op_sel_hi:[1,0,1]
	v_pk_fma_f32 v[36:37], v[68:69], v[14:15], v[36:37] op_sel:[0,0,0] op_sel_hi:[1,0,1]
	v_pk_fma_f32 v[38:39], v[70:71], v[14:15], v[38:39] op_sel:[0,0,0] op_sel_hi:[1,0,1]
	v_pk_fma_f32 v[40:41], v[72:73], v[14:15], v[40:41] op_sel:[0,0,0] op_sel_hi:[1,0,1]
	ds_read_b128 v[46:49], v1 offset:44912
	ds_read_b128 v[50:53], v1 offset:44928
	ds_read_b128 v[54:57], v1 offset:44944
	ds_read_b128 v[58:61], v1 offset:44960
	ds_read_b128 v[62:65], v1 offset:44976
	ds_read_b128 v[66:69], v1 offset:44992
	ds_read_b128 v[70:73], v1 offset:45008
	s_waitcnt lgkmcnt(0)
	v_pk_fma_f32 v[16:17], v[80:81], v[14:15], v[16:17] op_sel:[0,1,0] op_sel_hi:[1,1,1]
	v_pk_fma_f32 v[18:19], v[82:83], v[14:15], v[18:19] op_sel:[0,1,0] op_sel_hi:[1,1,1]
	v_pk_fma_f32 v[20:21], v[84:85], v[14:15], v[20:21] op_sel:[0,1,0] op_sel_hi:[1,1,1]
	v_pk_fma_f32 v[22:23], v[86:87], v[14:15], v[22:23] op_sel:[0,1,0] op_sel_hi:[1,1,1]
	v_pk_fma_f32 v[24:25], v[88:89], v[14:15], v[24:25] op_sel:[0,1,0] op_sel_hi:[1,1,1]
	v_pk_fma_f32 v[26:27], v[226:227], v[14:15], v[26:27] op_sel:[0,1,0] op_sel_hi:[1,1,1]
	v_pk_fma_f32 v[28:29], v[228:229], v[14:15], v[28:29] op_sel:[0,1,0] op_sel_hi:[1,1,1]
	v_pk_fma_f32 v[30:31], v[230:231], v[14:15], v[30:31] op_sel:[0,1,0] op_sel_hi:[1,1,1]
	v_pk_fma_f32 v[32:33], v[232:233], v[14:15], v[32:33] op_sel:[0,1,0] op_sel_hi:[1,1,1]
	v_pk_fma_f32 v[34:35], v[234:235], v[14:15], v[34:35] op_sel:[0,1,0] op_sel_hi:[1,1,1]
	v_pk_fma_f32 v[36:37], v[236:237], v[14:15], v[36:37] op_sel:[0,1,0] op_sel_hi:[1,1,1]
	v_pk_fma_f32 v[38:39], v[238:239], v[14:15], v[38:39] op_sel:[0,1,0] op_sel_hi:[1,1,1]
	v_pk_fma_f32 v[40:41], v[240:241], v[14:15], v[40:41] op_sel:[0,1,0] op_sel_hi:[1,1,1]
	ds_read_b128 v[82:85], v1 offset:45072
	ds_read_b128 v[86:89], v1 offset:45088
	ds_read_b128 v[226:229], v1 offset:45104
	ds_read_b128 v[230:233], v1 offset:45120
	ds_read_b128 v[234:237], v1 offset:45136
	ds_read_b128 v[238:241], v1 offset:45152
	s_waitcnt lgkmcnt(0)
	v_fmac_f32_e32 v17, v49, v16
	v_pk_fma_f32 v[18:19], v[50:51], v[16:17], v[18:19] op_sel:[0,0,0] op_sel_hi:[1,0,1]
	v_pk_fma_f32 v[20:21], v[52:53], v[16:17], v[20:21] op_sel:[0,0,0] op_sel_hi:[1,0,1]
	v_pk_fma_f32 v[22:23], v[54:55], v[16:17], v[22:23] op_sel:[0,0,0] op_sel_hi:[1,0,1]
	v_pk_fma_f32 v[24:25], v[56:57], v[16:17], v[24:25] op_sel:[0,0,0] op_sel_hi:[1,0,1]
	v_pk_fma_f32 v[26:27], v[58:59], v[16:17], v[26:27] op_sel:[0,0,0] op_sel_hi:[1,0,1]
	v_pk_fma_f32 v[28:29], v[60:61], v[16:17], v[28:29] op_sel:[0,0,0] op_sel_hi:[1,0,1]
	v_pk_fma_f32 v[30:31], v[62:63], v[16:17], v[30:31] op_sel:[0,0,0] op_sel_hi:[1,0,1]
	v_pk_fma_f32 v[32:33], v[64:65], v[16:17], v[32:33] op_sel:[0,0,0] op_sel_hi:[1,0,1]
	v_pk_fma_f32 v[34:35], v[66:67], v[16:17], v[34:35] op_sel:[0,0,0] op_sel_hi:[1,0,1]
	v_pk_fma_f32 v[36:37], v[68:69], v[16:17], v[36:37] op_sel:[0,0,0] op_sel_hi:[1,0,1]
	v_pk_fma_f32 v[38:39], v[70:71], v[16:17], v[38:39] op_sel:[0,0,0] op_sel_hi:[1,0,1]
	v_pk_fma_f32 v[40:41], v[72:73], v[16:17], v[40:41] op_sel:[0,0,0] op_sel_hi:[1,0,1]
	ds_read_b128 v[50:53], v1 offset:45216
	ds_read_b128 v[54:57], v1 offset:45232
	ds_read_b128 v[58:61], v1 offset:45248
	ds_read_b128 v[62:65], v1 offset:45264
	ds_read_b128 v[66:69], v1 offset:45280
	ds_read_b128 v[70:73], v1 offset:45296
	s_waitcnt lgkmcnt(0)
	v_pk_fma_f32 v[18:19], v[82:83], v[16:17], v[18:19] op_sel:[0,1,0] op_sel_hi:[1,1,1]
	v_pk_fma_f32 v[20:21], v[84:85], v[16:17], v[20:21] op_sel:[0,1,0] op_sel_hi:[1,1,1]
	v_pk_fma_f32 v[22:23], v[86:87], v[16:17], v[22:23] op_sel:[0,1,0] op_sel_hi:[1,1,1]
	v_pk_fma_f32 v[24:25], v[88:89], v[16:17], v[24:25] op_sel:[0,1,0] op_sel_hi:[1,1,1]
	v_pk_fma_f32 v[26:27], v[226:227], v[16:17], v[26:27] op_sel:[0,1,0] op_sel_hi:[1,1,1]
	v_pk_fma_f32 v[28:29], v[228:229], v[16:17], v[28:29] op_sel:[0,1,0] op_sel_hi:[1,1,1]
	v_pk_fma_f32 v[30:31], v[230:231], v[16:17], v[30:31] op_sel:[0,1,0] op_sel_hi:[1,1,1]
	v_pk_fma_f32 v[32:33], v[232:233], v[16:17], v[32:33] op_sel:[0,1,0] op_sel_hi:[1,1,1]
	v_pk_fma_f32 v[34:35], v[234:235], v[16:17], v[34:35] op_sel:[0,1,0] op_sel_hi:[1,1,1]
	v_pk_fma_f32 v[36:37], v[236:237], v[16:17], v[36:37] op_sel:[0,1,0] op_sel_hi:[1,1,1]
	v_pk_fma_f32 v[38:39], v[238:239], v[16:17], v[38:39] op_sel:[0,1,0] op_sel_hi:[1,1,1]
	v_pk_fma_f32 v[40:41], v[240:241], v[16:17], v[40:41] op_sel:[0,1,0] op_sel_hi:[1,1,1]
	ds_read_b128 v[82:85], v1 offset:45360
	ds_read_b128 v[86:89], v1 offset:45376
	ds_read_b128 v[226:229], v1 offset:45392
	ds_read_b128 v[230:233], v1 offset:45408
	ds_read_b128 v[234:237], v1 offset:45424
	ds_read_b128 v[238:241], v1 offset:45440
	s_waitcnt lgkmcnt(0)
	v_fmac_f32_e32 v19, v51, v18
	v_pk_fma_f32 v[20:21], v[52:53], v[18:19], v[20:21] op_sel:[0,0,0] op_sel_hi:[1,0,1]
	v_pk_fma_f32 v[22:23], v[54:55], v[18:19], v[22:23] op_sel:[0,0,0] op_sel_hi:[1,0,1]
	v_pk_fma_f32 v[24:25], v[56:57], v[18:19], v[24:25] op_sel:[0,0,0] op_sel_hi:[1,0,1]
	v_pk_fma_f32 v[26:27], v[58:59], v[18:19], v[26:27] op_sel:[0,0,0] op_sel_hi:[1,0,1]
	v_pk_fma_f32 v[28:29], v[60:61], v[18:19], v[28:29] op_sel:[0,0,0] op_sel_hi:[1,0,1]
	v_pk_fma_f32 v[30:31], v[62:63], v[18:19], v[30:31] op_sel:[0,0,0] op_sel_hi:[1,0,1]
	v_pk_fma_f32 v[32:33], v[64:65], v[18:19], v[32:33] op_sel:[0,0,0] op_sel_hi:[1,0,1]
	v_pk_fma_f32 v[34:35], v[66:67], v[18:19], v[34:35] op_sel:[0,0,0] op_sel_hi:[1,0,1]
	v_pk_fma_f32 v[36:37], v[68:69], v[18:19], v[36:37] op_sel:[0,0,0] op_sel_hi:[1,0,1]
	v_pk_fma_f32 v[38:39], v[70:71], v[18:19], v[38:39] op_sel:[0,0,0] op_sel_hi:[1,0,1]
	v_pk_fma_f32 v[40:41], v[72:73], v[18:19], v[40:41] op_sel:[0,0,0] op_sel_hi:[1,0,1]
	ds_read_b128 v[50:53], v1 offset:45504
	ds_read_b128 v[54:57], v1 offset:45520
	ds_read_b128 v[58:61], v1 offset:45536
	ds_read_b128 v[62:65], v1 offset:45552
	ds_read_b128 v[66:69], v1 offset:45568
	ds_read_b128 v[70:73], v1 offset:45584
	s_waitcnt lgkmcnt(0)
	v_pk_fma_f32 v[20:21], v[84:85], v[18:19], v[20:21] op_sel:[0,1,0] op_sel_hi:[1,1,1]
	v_pk_fma_f32 v[22:23], v[86:87], v[18:19], v[22:23] op_sel:[0,1,0] op_sel_hi:[1,1,1]
	v_pk_fma_f32 v[24:25], v[88:89], v[18:19], v[24:25] op_sel:[0,1,0] op_sel_hi:[1,1,1]
	v_pk_fma_f32 v[26:27], v[226:227], v[18:19], v[26:27] op_sel:[0,1,0] op_sel_hi:[1,1,1]
	v_pk_fma_f32 v[28:29], v[228:229], v[18:19], v[28:29] op_sel:[0,1,0] op_sel_hi:[1,1,1]
	v_pk_fma_f32 v[30:31], v[230:231], v[18:19], v[30:31] op_sel:[0,1,0] op_sel_hi:[1,1,1]
	v_pk_fma_f32 v[32:33], v[232:233], v[18:19], v[32:33] op_sel:[0,1,0] op_sel_hi:[1,1,1]
	v_pk_fma_f32 v[34:35], v[234:235], v[18:19], v[34:35] op_sel:[0,1,0] op_sel_hi:[1,1,1]
	v_pk_fma_f32 v[36:37], v[236:237], v[18:19], v[36:37] op_sel:[0,1,0] op_sel_hi:[1,1,1]
	v_pk_fma_f32 v[38:39], v[238:239], v[18:19], v[38:39] op_sel:[0,1,0] op_sel_hi:[1,1,1]
	v_pk_fma_f32 v[40:41], v[240:241], v[18:19], v[40:41] op_sel:[0,1,0] op_sel_hi:[1,1,1]
	ds_read_b128 v[86:89], v1 offset:45664
	ds_read_b128 v[226:229], v1 offset:45680
	ds_read_b128 v[230:233], v1 offset:45696
	ds_read_b128 v[234:237], v1 offset:45712
	ds_read_b128 v[238:241], v1 offset:45728
	s_waitcnt lgkmcnt(0)
	v_fmac_f32_e32 v21, v53, v20
	v_pk_fma_f32 v[22:23], v[54:55], v[20:21], v[22:23] op_sel:[0,0,0] op_sel_hi:[1,0,1]
	v_pk_fma_f32 v[24:25], v[56:57], v[20:21], v[24:25] op_sel:[0,0,0] op_sel_hi:[1,0,1]
	v_pk_fma_f32 v[26:27], v[58:59], v[20:21], v[26:27] op_sel:[0,0,0] op_sel_hi:[1,0,1]
	v_pk_fma_f32 v[28:29], v[60:61], v[20:21], v[28:29] op_sel:[0,0,0] op_sel_hi:[1,0,1]
	v_pk_fma_f32 v[30:31], v[62:63], v[20:21], v[30:31] op_sel:[0,0,0] op_sel_hi:[1,0,1]
	v_pk_fma_f32 v[32:33], v[64:65], v[20:21], v[32:33] op_sel:[0,0,0] op_sel_hi:[1,0,1]
	v_pk_fma_f32 v[34:35], v[66:67], v[20:21], v[34:35] op_sel:[0,0,0] op_sel_hi:[1,0,1]
	v_pk_fma_f32 v[36:37], v[68:69], v[20:21], v[36:37] op_sel:[0,0,0] op_sel_hi:[1,0,1]
	v_pk_fma_f32 v[38:39], v[70:71], v[20:21], v[38:39] op_sel:[0,0,0] op_sel_hi:[1,0,1]
	v_pk_fma_f32 v[40:41], v[72:73], v[20:21], v[40:41] op_sel:[0,0,0] op_sel_hi:[1,0,1]
	ds_read_b128 v[54:57], v1 offset:45808
	ds_read_b128 v[58:61], v1 offset:45824
	ds_read_b128 v[62:65], v1 offset:45840
	ds_read_b128 v[66:69], v1 offset:45856
	ds_read_b128 v[70:73], v1 offset:45872
	s_waitcnt lgkmcnt(0)
	v_pk_fma_f32 v[22:23], v[86:87], v[20:21], v[22:23] op_sel:[0,1,0] op_sel_hi:[1,1,1]
	v_pk_fma_f32 v[24:25], v[88:89], v[20:21], v[24:25] op_sel:[0,1,0] op_sel_hi:[1,1,1]
	v_pk_fma_f32 v[26:27], v[226:227], v[20:21], v[26:27] op_sel:[0,1,0] op_sel_hi:[1,1,1]
	v_pk_fma_f32 v[28:29], v[228:229], v[20:21], v[28:29] op_sel:[0,1,0] op_sel_hi:[1,1,1]
	v_pk_fma_f32 v[30:31], v[230:231], v[20:21], v[30:31] op_sel:[0,1,0] op_sel_hi:[1,1,1]
	v_pk_fma_f32 v[32:33], v[232:233], v[20:21], v[32:33] op_sel:[0,1,0] op_sel_hi:[1,1,1]
	v_pk_fma_f32 v[34:35], v[234:235], v[20:21], v[34:35] op_sel:[0,1,0] op_sel_hi:[1,1,1]
	v_pk_fma_f32 v[36:37], v[236:237], v[20:21], v[36:37] op_sel:[0,1,0] op_sel_hi:[1,1,1]
	v_pk_fma_f32 v[38:39], v[238:239], v[20:21], v[38:39] op_sel:[0,1,0] op_sel_hi:[1,1,1]
	v_pk_fma_f32 v[40:41], v[240:241], v[20:21], v[40:41] op_sel:[0,1,0] op_sel_hi:[1,1,1]
	ds_read_b128 v[86:89], v1 offset:45952
	ds_read_b128 v[226:229], v1 offset:45968
	ds_read_b128 v[230:233], v1 offset:45984
	ds_read_b128 v[234:237], v1 offset:46000
	ds_read_b128 v[238:241], v1 offset:46016
	s_waitcnt lgkmcnt(0)
	v_fmac_f32_e32 v23, v55, v22
	v_pk_fma_f32 v[24:25], v[56:57], v[22:23], v[24:25] op_sel:[0,0,0] op_sel_hi:[1,0,1]
	v_pk_fma_f32 v[26:27], v[58:59], v[22:23], v[26:27] op_sel:[0,0,0] op_sel_hi:[1,0,1]
	v_pk_fma_f32 v[28:29], v[60:61], v[22:23], v[28:29] op_sel:[0,0,0] op_sel_hi:[1,0,1]
	v_pk_fma_f32 v[30:31], v[62:63], v[22:23], v[30:31] op_sel:[0,0,0] op_sel_hi:[1,0,1]
	v_pk_fma_f32 v[32:33], v[64:65], v[22:23], v[32:33] op_sel:[0,0,0] op_sel_hi:[1,0,1]
	v_pk_fma_f32 v[34:35], v[66:67], v[22:23], v[34:35] op_sel:[0,0,0] op_sel_hi:[1,0,1]
	v_pk_fma_f32 v[36:37], v[68:69], v[22:23], v[36:37] op_sel:[0,0,0] op_sel_hi:[1,0,1]
	v_pk_fma_f32 v[38:39], v[70:71], v[22:23], v[38:39] op_sel:[0,0,0] op_sel_hi:[1,0,1]
	v_pk_fma_f32 v[40:41], v[72:73], v[22:23], v[40:41] op_sel:[0,0,0] op_sel_hi:[1,0,1]
	ds_read_b128 v[54:57], v1 offset:46096
	ds_read_b128 v[58:61], v1 offset:46112
	ds_read_b128 v[62:65], v1 offset:46128
	ds_read_b128 v[66:69], v1 offset:46144
	ds_read_b128 v[70:73], v1 offset:46160
	s_waitcnt lgkmcnt(0)
	v_pk_fma_f32 v[24:25], v[88:89], v[22:23], v[24:25] op_sel:[0,1,0] op_sel_hi:[1,1,1]
	v_pk_fma_f32 v[26:27], v[226:227], v[22:23], v[26:27] op_sel:[0,1,0] op_sel_hi:[1,1,1]
	v_pk_fma_f32 v[28:29], v[228:229], v[22:23], v[28:29] op_sel:[0,1,0] op_sel_hi:[1,1,1]
	v_pk_fma_f32 v[30:31], v[230:231], v[22:23], v[30:31] op_sel:[0,1,0] op_sel_hi:[1,1,1]
	v_pk_fma_f32 v[32:33], v[232:233], v[22:23], v[32:33] op_sel:[0,1,0] op_sel_hi:[1,1,1]
	v_pk_fma_f32 v[34:35], v[234:235], v[22:23], v[34:35] op_sel:[0,1,0] op_sel_hi:[1,1,1]
	v_pk_fma_f32 v[36:37], v[236:237], v[22:23], v[36:37] op_sel:[0,1,0] op_sel_hi:[1,1,1]
	v_pk_fma_f32 v[38:39], v[238:239], v[22:23], v[38:39] op_sel:[0,1,0] op_sel_hi:[1,1,1]
	v_pk_fma_f32 v[40:41], v[240:241], v[22:23], v[40:41] op_sel:[0,1,0] op_sel_hi:[1,1,1]
	ds_read_b128 v[226:229], v1 offset:46256
	ds_read_b128 v[230:233], v1 offset:46272
	ds_read_b128 v[234:237], v1 offset:46288
	ds_read_b128 v[238:241], v1 offset:46304
	s_waitcnt lgkmcnt(0)
	v_fmac_f32_e32 v25, v57, v24
	v_pk_fma_f32 v[26:27], v[58:59], v[24:25], v[26:27] op_sel:[0,0,0] op_sel_hi:[1,0,1]
	v_pk_fma_f32 v[28:29], v[60:61], v[24:25], v[28:29] op_sel:[0,0,0] op_sel_hi:[1,0,1]
	v_pk_fma_f32 v[30:31], v[62:63], v[24:25], v[30:31] op_sel:[0,0,0] op_sel_hi:[1,0,1]
	v_pk_fma_f32 v[32:33], v[64:65], v[24:25], v[32:33] op_sel:[0,0,0] op_sel_hi:[1,0,1]
	v_pk_fma_f32 v[34:35], v[66:67], v[24:25], v[34:35] op_sel:[0,0,0] op_sel_hi:[1,0,1]
	v_pk_fma_f32 v[36:37], v[68:69], v[24:25], v[36:37] op_sel:[0,0,0] op_sel_hi:[1,0,1]
	v_pk_fma_f32 v[38:39], v[70:71], v[24:25], v[38:39] op_sel:[0,0,0] op_sel_hi:[1,0,1]
	v_pk_fma_f32 v[40:41], v[72:73], v[24:25], v[40:41] op_sel:[0,0,0] op_sel_hi:[1,0,1]
	ds_read_b128 v[58:61], v1 offset:46400
	ds_read_b128 v[62:65], v1 offset:46416
	ds_read_b128 v[66:69], v1 offset:46432
	ds_read_b128 v[70:73], v1 offset:46448
	s_waitcnt lgkmcnt(0)
	v_pk_fma_f32 v[26:27], v[226:227], v[24:25], v[26:27] op_sel:[0,1,0] op_sel_hi:[1,1,1]
	v_pk_fma_f32 v[28:29], v[228:229], v[24:25], v[28:29] op_sel:[0,1,0] op_sel_hi:[1,1,1]
	v_pk_fma_f32 v[30:31], v[230:231], v[24:25], v[30:31] op_sel:[0,1,0] op_sel_hi:[1,1,1]
	v_pk_fma_f32 v[32:33], v[232:233], v[24:25], v[32:33] op_sel:[0,1,0] op_sel_hi:[1,1,1]
	v_pk_fma_f32 v[34:35], v[234:235], v[24:25], v[34:35] op_sel:[0,1,0] op_sel_hi:[1,1,1]
	v_pk_fma_f32 v[36:37], v[236:237], v[24:25], v[36:37] op_sel:[0,1,0] op_sel_hi:[1,1,1]
	v_pk_fma_f32 v[38:39], v[238:239], v[24:25], v[38:39] op_sel:[0,1,0] op_sel_hi:[1,1,1]
	v_pk_fma_f32 v[40:41], v[240:241], v[24:25], v[40:41] op_sel:[0,1,0] op_sel_hi:[1,1,1]
	ds_read_b128 v[226:229], v1 offset:46544
	ds_read_b128 v[230:233], v1 offset:46560
	ds_read_b128 v[234:237], v1 offset:46576
	ds_read_b128 v[238:241], v1 offset:46592
	s_waitcnt lgkmcnt(0)
	v_fmac_f32_e32 v27, v59, v26
	v_pk_fma_f32 v[28:29], v[60:61], v[26:27], v[28:29] op_sel:[0,0,0] op_sel_hi:[1,0,1]
	v_pk_fma_f32 v[30:31], v[62:63], v[26:27], v[30:31] op_sel:[0,0,0] op_sel_hi:[1,0,1]
	v_pk_fma_f32 v[32:33], v[64:65], v[26:27], v[32:33] op_sel:[0,0,0] op_sel_hi:[1,0,1]
	v_pk_fma_f32 v[34:35], v[66:67], v[26:27], v[34:35] op_sel:[0,0,0] op_sel_hi:[1,0,1]
	v_pk_fma_f32 v[36:37], v[68:69], v[26:27], v[36:37] op_sel:[0,0,0] op_sel_hi:[1,0,1]
	v_pk_fma_f32 v[38:39], v[70:71], v[26:27], v[38:39] op_sel:[0,0,0] op_sel_hi:[1,0,1]
	v_pk_fma_f32 v[40:41], v[72:73], v[26:27], v[40:41] op_sel:[0,0,0] op_sel_hi:[1,0,1]
	ds_read_b128 v[58:61], v1 offset:46688
	ds_read_b128 v[62:65], v1 offset:46704
	ds_read_b128 v[66:69], v1 offset:46720
	ds_read_b128 v[70:73], v1 offset:46736
	s_waitcnt lgkmcnt(0)
	v_pk_fma_f32 v[28:29], v[228:229], v[26:27], v[28:29] op_sel:[0,1,0] op_sel_hi:[1,1,1]
	v_pk_fma_f32 v[30:31], v[230:231], v[26:27], v[30:31] op_sel:[0,1,0] op_sel_hi:[1,1,1]
	v_pk_fma_f32 v[32:33], v[232:233], v[26:27], v[32:33] op_sel:[0,1,0] op_sel_hi:[1,1,1]
	v_pk_fma_f32 v[34:35], v[234:235], v[26:27], v[34:35] op_sel:[0,1,0] op_sel_hi:[1,1,1]
	v_pk_fma_f32 v[36:37], v[236:237], v[26:27], v[36:37] op_sel:[0,1,0] op_sel_hi:[1,1,1]
	v_pk_fma_f32 v[38:39], v[238:239], v[26:27], v[38:39] op_sel:[0,1,0] op_sel_hi:[1,1,1]
	v_pk_fma_f32 v[40:41], v[240:241], v[26:27], v[40:41] op_sel:[0,1,0] op_sel_hi:[1,1,1]
	ds_read_b128 v[230:233], v1 offset:46848
	ds_read_b128 v[234:237], v1 offset:46864
	ds_read_b128 v[238:241], v1 offset:46880
	s_waitcnt lgkmcnt(0)
	v_fmac_f32_e32 v29, v61, v28
	v_pk_fma_f32 v[30:31], v[62:63], v[28:29], v[30:31] op_sel:[0,0,0] op_sel_hi:[1,0,1]
	v_pk_fma_f32 v[32:33], v[64:65], v[28:29], v[32:33] op_sel:[0,0,0] op_sel_hi:[1,0,1]
	v_pk_fma_f32 v[34:35], v[66:67], v[28:29], v[34:35] op_sel:[0,0,0] op_sel_hi:[1,0,1]
	v_pk_fma_f32 v[36:37], v[68:69], v[28:29], v[36:37] op_sel:[0,0,0] op_sel_hi:[1,0,1]
	v_pk_fma_f32 v[38:39], v[70:71], v[28:29], v[38:39] op_sel:[0,0,0] op_sel_hi:[1,0,1]
	v_pk_fma_f32 v[40:41], v[72:73], v[28:29], v[40:41] op_sel:[0,0,0] op_sel_hi:[1,0,1]
	ds_read_b128 v[62:65], v1 offset:46992
	ds_read_b128 v[66:69], v1 offset:47008
	ds_read_b128 v[70:73], v1 offset:47024
	s_waitcnt lgkmcnt(0)
	v_pk_fma_f32 v[30:31], v[230:231], v[28:29], v[30:31] op_sel:[0,1,0] op_sel_hi:[1,1,1]
	v_pk_fma_f32 v[32:33], v[232:233], v[28:29], v[32:33] op_sel:[0,1,0] op_sel_hi:[1,1,1]
	v_pk_fma_f32 v[34:35], v[234:235], v[28:29], v[34:35] op_sel:[0,1,0] op_sel_hi:[1,1,1]
	v_pk_fma_f32 v[36:37], v[236:237], v[28:29], v[36:37] op_sel:[0,1,0] op_sel_hi:[1,1,1]
	v_pk_fma_f32 v[38:39], v[238:239], v[28:29], v[38:39] op_sel:[0,1,0] op_sel_hi:[1,1,1]
	v_pk_fma_f32 v[40:41], v[240:241], v[28:29], v[40:41] op_sel:[0,1,0] op_sel_hi:[1,1,1]
	ds_read_b128 v[230:233], v1 offset:47136
	ds_read_b128 v[234:237], v1 offset:47152
	ds_read_b128 v[238:241], v1 offset:47168
	s_waitcnt lgkmcnt(0)
	v_fmac_f32_e32 v31, v63, v30
	v_pk_fma_f32 v[32:33], v[64:65], v[30:31], v[32:33] op_sel:[0,0,0] op_sel_hi:[1,0,1]
	v_pk_fma_f32 v[34:35], v[66:67], v[30:31], v[34:35] op_sel:[0,0,0] op_sel_hi:[1,0,1]
	v_pk_fma_f32 v[36:37], v[68:69], v[30:31], v[36:37] op_sel:[0,0,0] op_sel_hi:[1,0,1]
	v_pk_fma_f32 v[38:39], v[70:71], v[30:31], v[38:39] op_sel:[0,0,0] op_sel_hi:[1,0,1]
	v_pk_fma_f32 v[40:41], v[72:73], v[30:31], v[40:41] op_sel:[0,0,0] op_sel_hi:[1,0,1]
	ds_read_b128 v[62:65], v1 offset:47280
	ds_read_b128 v[66:69], v1 offset:47296
	ds_read_b128 v[70:73], v1 offset:47312
	s_waitcnt lgkmcnt(0)
	v_pk_fma_f32 v[32:33], v[232:233], v[30:31], v[32:33] op_sel:[0,1,0] op_sel_hi:[1,1,1]
	v_pk_fma_f32 v[34:35], v[234:235], v[30:31], v[34:35] op_sel:[0,1,0] op_sel_hi:[1,1,1]
	v_pk_fma_f32 v[36:37], v[236:237], v[30:31], v[36:37] op_sel:[0,1,0] op_sel_hi:[1,1,1]
	v_pk_fma_f32 v[38:39], v[238:239], v[30:31], v[38:39] op_sel:[0,1,0] op_sel_hi:[1,1,1]
	v_pk_fma_f32 v[40:41], v[240:241], v[30:31], v[40:41] op_sel:[0,1,0] op_sel_hi:[1,1,1]
	ds_read_b128 v[234:237], v1 offset:47440
	ds_read_b128 v[238:241], v1 offset:47456
	s_waitcnt lgkmcnt(0)
	v_fmac_f32_e32 v33, v65, v32
	v_pk_fma_f32 v[34:35], v[66:67], v[32:33], v[34:35] op_sel:[0,0,0] op_sel_hi:[1,0,1]
	v_pk_fma_f32 v[36:37], v[68:69], v[32:33], v[36:37] op_sel:[0,0,0] op_sel_hi:[1,0,1]
	v_pk_fma_f32 v[38:39], v[70:71], v[32:33], v[38:39] op_sel:[0,0,0] op_sel_hi:[1,0,1]
	v_pk_fma_f32 v[40:41], v[72:73], v[32:33], v[40:41] op_sel:[0,0,0] op_sel_hi:[1,0,1]
	ds_read_b128 v[66:69], v1 offset:47584
	ds_read_b128 v[70:73], v1 offset:47600
	s_waitcnt lgkmcnt(0)
	v_pk_fma_f32 v[34:35], v[234:235], v[32:33], v[34:35] op_sel:[0,1,0] op_sel_hi:[1,1,1]
	v_pk_fma_f32 v[36:37], v[236:237], v[32:33], v[36:37] op_sel:[0,1,0] op_sel_hi:[1,1,1]
	v_pk_fma_f32 v[38:39], v[238:239], v[32:33], v[38:39] op_sel:[0,1,0] op_sel_hi:[1,1,1]
	v_pk_fma_f32 v[40:41], v[240:241], v[32:33], v[40:41] op_sel:[0,1,0] op_sel_hi:[1,1,1]
	ds_read_b128 v[234:237], v1 offset:47728
	ds_read_b128 v[238:241], v1 offset:47744
	s_waitcnt lgkmcnt(0)
	v_fmac_f32_e32 v35, v67, v34
	v_pk_fma_f32 v[36:37], v[68:69], v[34:35], v[36:37] op_sel:[0,0,0] op_sel_hi:[1,0,1]
	v_pk_fma_f32 v[38:39], v[70:71], v[34:35], v[38:39] op_sel:[0,0,0] op_sel_hi:[1,0,1]
	v_pk_fma_f32 v[40:41], v[72:73], v[34:35], v[40:41] op_sel:[0,0,0] op_sel_hi:[1,0,1]
	ds_read_b128 v[66:69], v1 offset:47872
	ds_read_b128 v[70:73], v1 offset:47888
	s_waitcnt lgkmcnt(0)
	v_pk_fma_f32 v[36:37], v[236:237], v[34:35], v[36:37] op_sel:[0,1,0] op_sel_hi:[1,1,1]
	v_pk_fma_f32 v[38:39], v[238:239], v[34:35], v[38:39] op_sel:[0,1,0] op_sel_hi:[1,1,1]
	v_pk_fma_f32 v[40:41], v[240:241], v[34:35], v[40:41] op_sel:[0,1,0] op_sel_hi:[1,1,1]
	ds_read_b128 v[238:241], v1 offset:48032
	s_waitcnt lgkmcnt(0)
	v_fmac_f32_e32 v37, v69, v36
	v_pk_fma_f32 v[38:39], v[70:71], v[36:37], v[38:39] op_sel:[0,0,0] op_sel_hi:[1,0,1]
	v_pk_fma_f32 v[40:41], v[72:73], v[36:37], v[40:41] op_sel:[0,0,0] op_sel_hi:[1,0,1]
	ds_read_b128 v[70:73], v1 offset:48176
	s_waitcnt lgkmcnt(0)
	v_pk_fma_f32 v[38:39], v[238:239], v[36:37], v[38:39] op_sel:[0,1,0] op_sel_hi:[1,1,1]
	v_pk_fma_f32 v[40:41], v[240:241], v[36:37], v[40:41] op_sel:[0,1,0] op_sel_hi:[1,1,1]
	ds_read_b128 v[238:241], v1 offset:48320
	s_waitcnt lgkmcnt(0)
	v_fmac_f32_e32 v39, v71, v38
	v_pk_fma_f32 v[40:41], v[72:73], v[38:39], v[40:41] op_sel:[0,0,0] op_sel_hi:[1,0,1]
	ds_read_b128 v[70:73], v1 offset:48464
	s_waitcnt lgkmcnt(0)
	v_pk_fma_f32 v[40:41], v[240:241], v[38:39], v[40:41] op_sel:[0,1,0] op_sel_hi:[1,1,1]
	s_waitcnt lgkmcnt(0)
	v_fmac_f32_e32 v41, v73, v40
	ds_write2_b32 v135, v10, v11 offset0:0 offset1:36
	ds_write2_b32 v135, v12, v13 offset0:72 offset1:108
	ds_write2_b32 v135, v14, v15 offset0:144 offset1:180
	ds_write2_b32 v135, v16, v17 offset0:216 offset1:252
	ds_write2_b32 v245, v18, v19 offset0:0 offset1:36
	ds_write2_b32 v245, v20, v21 offset0:72 offset1:108
	ds_write2_b32 v245, v22, v23 offset0:144 offset1:180
	ds_write2_b32 v245, v24, v25 offset0:216 offset1:252
	ds_write2_b32 v246, v26, v27 offset0:0 offset1:36
	ds_write2_b32 v246, v28, v29 offset0:72 offset1:108
	ds_write2_b32 v246, v30, v31 offset0:144 offset1:180
	ds_write2_b32 v246, v32, v33 offset0:216 offset1:252
	ds_write2_b32 v247, v34, v35 offset0:0 offset1:36
	ds_write2_b32 v247, v36, v37 offset0:72 offset1:108
	ds_write2_b32 v247, v38, v39 offset0:144 offset1:180
	ds_write2_b32 v247, v40, v41 offset0:216 offset1:252
	s_mov_b32 exec_hi, -1
	s_branch .Ldc_b3

.Ldc_s2q:
	s_cmp_eq_u32 s60, 2
	s_cbranch_scc1 .Ldc_q2
	s_and_b32 s61, s60, 1
	s_lshl_b32 s61, s61, 6
	v_mul_u32_u24_e32 v244, 0x840, v223
	v_lshl_add_u32 v244, v222, 2, v244
	s_add_i32 s61, s61, 0x11600
	v_add_u32_e32 v244, s61, v244
	v_add_u32_e32 v245, 0x420, v244
	ds_read2_b32 v[10:11], v244 offset0:0 offset1:33
	ds_read2_b32 v[12:13], v244 offset0:66 offset1:99
	ds_read2_b32 v[14:15], v244 offset0:132 offset1:165
	ds_read2_b32 v[16:17], v244 offset0:198 offset1:231
	ds_read2_b32 v[18:19], v245 offset0:0 offset1:33
	ds_read2_b32 v[20:21], v245 offset0:66 offset1:99
	ds_read2_b32 v[22:23], v245 offset0:132 offset1:165
	ds_read2_b32 v[24:25], v245 offset0:198 offset1:231

.Ldc_b3:
	s_waitcnt lgkmcnt(0)
	s_barrier
	s_cmp_lt_u32 s60, 2
	s_cbranch_scc1 .Ldc_s4w
	s_and_b32 s61, s60, 1
	s_lshl_b32 s61, s61, 6
	v_mul_u32_u24_e32 v244, 0x480, v223
	v_lshl_add_u32 v244, v222, 2, v244
	v_add_u32_e32 v244, s61, v244
	v_add_u32_e32 v244, 0xe200, v244
	ds_read2_b32 v[34:35], v244 offset0:0 offset1:36
	ds_read2_b32 v[36:37], v244 offset0:72 offset1:108
	ds_read2_b32 v[38:39], v244 offset0:144 offset1:180
	ds_read2_b32 v[40:41], v244 offset0:216 offset1:252
	v_mul_u32_u24_e32 v245, 0x90, v222
	v_lshl_add_u32 v245, v223, 5, v245
	ds_read_b128 v[26:29], v245 offset:48640
	ds_read_b128 v[30:33], v245 offset:48656
	s_waitcnt lgkmcnt(0)
	v_mfma_f32_16x16x4_f32 v[58:61], v26, v34, v[58:61]
	v_mfma_f32_16x16x4_f32 v[58:61], v27, v35, v[58:61]
	v_mfma_f32_16x16x4_f32 v[58:61], v28, v36, v[58:61]
	v_mfma_f32_16x16x4_f32 v[58:61], v29, v37, v[58:61]
	v_mfma_f32_16x16x4_f32 v[58:61], v30, v38, v[58:61]
	v_mfma_f32_16x16x4_f32 v[58:61], v31, v39, v[58:61]
	v_mfma_f32_16x16x4_f32 v[58:61], v32, v40, v[58:61]
	v_mfma_f32_16x16x4_f32 v[58:61], v33, v41, v[58:61]
	ds_read_b128 v[26:29], v245 offset:50944
	ds_read_b128 v[30:33], v245 offset:50960
	s_waitcnt lgkmcnt(0)
	v_mfma_f32_16x16x4_f32 v[62:65], v26, v34, v[62:65]
	v_mfma_f32_16x16x4_f32 v[62:65], v27, v35, v[62:65]
	v_mfma_f32_16x16x4_f32 v[62:65], v28, v36, v[62:65]
	v_mfma_f32_16x16x4_f32 v[62:65], v29, v37, v[62:65]
	v_mfma_f32_16x16x4_f32 v[62:65], v30, v38, v[62:65]
	v_mfma_f32_16x16x4_f32 v[62:65], v31, v39, v[62:65]
	v_mfma_f32_16x16x4_f32 v[62:65], v32, v40, v[62:65]
	v_mfma_f32_16x16x4_f32 v[62:65], v33, v41, v[62:65]
	s_nop 7
	s_nop 3
	s_and_b32 s61, s60, 1
	s_lshl_b32 s61, s61, 6
	v_lshl_add_u32 v246, v223, 10, v248
	v_lshl_add_u32 v246, v222, 2, v246
	v_add_u32_e32 v246, s61, v246
	ds_write_b32 v246, v58 offset:17408
	ds_write_b32 v246, v59 offset:17664
	ds_write_b32 v246, v60 offset:17920
	ds_write_b32 v246, v61 offset:18176
	ds_write_b32 v246, v62 offset:21504
	ds_write_b32 v246, v63 offset:21760
	ds_write_b32 v246, v64 offset:22016
	ds_write_b32 v246, v65 offset:22272
	v_lshlrev_b32_e32 v245, 5, v223
	v_add_u32_e32 v245, 0x13780, v245
	ds_read_b128 v[42:45], v245
	ds_read_b128 v[46:49], v245 offset:16
	v_mov_b32_e32 v79, 0x1377c
	ds_read_b32 v78, v79
	v_mul_u32_u24_e32 v246, 0x880, v223
	v_lshl_add_u32 v246, v222, 2, v246
	s_and_b32 s61, s60, 1
	s_lshl_b32 s61, s61, 6
	s_add_i32 s61, s61, 0x11600
	v_mul_u32_u24_e32 v244, 0x210, v223
	v_lshl_add_u32 v244, v222, 2, v244
	v_add_u32_e32 v244, s61, v244
	ds_read_b32 v50, v246 offset:8896
	ds_read_b32 v51, v246 offset:9168
	ds_read_b32 v52, v246 offset:9440
	ds_read_b32 v53, v246 offset:9712
	ds_read_b32 v54, v246 offset:9984
	ds_read_b32 v55, v246 offset:10256
	ds_read_b32 v56, v246 offset:10528
	ds_read_b32 v57, v246 offset:10800
	ds_read_b32 v66, v244 offset:6336
	ds_read_b32 v67, v244 offset:6468
	ds_read_b32 v68, v244 offset:6600
	ds_read_b32 v69, v244 offset:6732
	s_waitcnt lgkmcnt(0)
	v_mul_f32_e32 v50, v42, v50
	v_mul_f32_e32 v51, v43, v51
	v_mul_f32_e32 v52, v44, v52
	v_mul_f32_e32 v53, v45, v53
	v_mul_f32_e32 v54, v46, v54
	v_mul_f32_e32 v55, v47, v55
	v_mul_f32_e32 v56, v48, v56
	v_mul_f32_e32 v57, v49, v57
	v_mul_f32_e32 v66, v78, v66
	v_mul_f32_e32 v67, v78, v67
	v_mul_f32_e32 v68, v78, v68
	v_mul_f32_e32 v69, v78, v69
	s_nop 1
	v_mfma_f32_16x16x4_f32 v[66:69], v50, v34, v[66:69]
	v_mfma_f32_16x16x4_f32 v[66:69], v51, v35, v[66:69]
	v_mfma_f32_16x16x4_f32 v[66:69], v52, v36, v[66:69]
	v_mfma_f32_16x16x4_f32 v[66:69], v53, v37, v[66:69]
	v_mfma_f32_16x16x4_f32 v[66:69], v54, v38, v[66:69]
	v_mfma_f32_16x16x4_f32 v[66:69], v55, v39, v[66:69]
	v_mfma_f32_16x16x4_f32 v[66:69], v56, v40, v[66:69]
	v_mfma_f32_16x16x4_f32 v[66:69], v57, v41, v[66:69]
	s_nop 7
	s_nop 3
	ds_write_b32 v244, v66 offset:6336
	ds_write_b32 v244, v67 offset:6468
	ds_write_b32 v244, v68 offset:6600
	ds_write_b32 v244, v69 offset:6732
	s_branch .Ldc_done
.Ldc_s4w:
	s_and_b32 s61, s60, 1
	s_lshl_b32 s61, s61, 6
	v_mul_u32_u24_e32 v244, 0x480, v223
	v_lshl_add_u32 v244, v222, 2, v244
	v_add_u32_e32 v244, s61, v244
	v_add_u32_e32 v244, 0xe200, v244
	ds_read2_b32 v[34:35], v244 offset0:0 offset1:36
	ds_read2_b32 v[36:37], v244 offset0:72 offset1:108
	ds_read2_b32 v[38:39], v244 offset0:144 offset1:180
	ds_read2_b32 v[40:41], v244 offset0:216 offset1:252
	v_lshlrev_b32_e32 v245, 5, v223
	v_add_u32_e32 v245, 0x13780, v245
	ds_read_b128 v[42:45], v245
	ds_read_b128 v[46:49], v245 offset:16
	v_mov_b32_e32 v79, 0x1377c
	ds_read_b32 v78, v79
	v_mul_u32_u24_e32 v246, 0x880, v223
	v_lshl_add_u32 v246, v222, 2, v246
	s_and_b32 s61, s60, 1
	s_lshl_b32 s61, s61, 6
	s_add_i32 s61, s61, 0x11600
	v_mul_u32_u24_e32 v244, 0x210, v223
	v_lshl_add_u32 v244, v222, 2, v244
	v_add_u32_e32 v244, s61, v244
	ds_read_b32 v26, v246 offset:8704
	ds_read_b32 v27, v246 offset:8976
	ds_read_b32 v28, v246 offset:9248
	ds_read_b32 v29, v246 offset:9520
	ds_read_b32 v30, v246 offset:9792
	ds_read_b32 v31, v246 offset:10064
	ds_read_b32 v32, v246 offset:10336
	ds_read_b32 v33, v246 offset:10608
	ds_read_b32 v66, v244 offset:0
	ds_read_b32 v67, v244 offset:132
	ds_read_b32 v68, v244 offset:264
	ds_read_b32 v69, v244 offset:396
	ds_read_b32 v50, v246 offset:8768
	ds_read_b32 v51, v246 offset:9040
	ds_read_b32 v52, v246 offset:9312
	ds_read_b32 v53, v246 offset:9584
	ds_read_b32 v54, v246 offset:9856
	ds_read_b32 v55, v246 offset:10128
	ds_read_b32 v56, v246 offset:10400
	ds_read_b32 v57, v246 offset:10672
	ds_read_b32 v70, v244 offset:2112
	ds_read_b32 v71, v244 offset:2244
	ds_read_b32 v72, v244 offset:2376
	ds_read_b32 v73, v244 offset:2508
	ds_read_b32 v58, v246 offset:8832
	ds_read_b32 v59, v246 offset:9104
	ds_read_b32 v60, v246 offset:9376
	ds_read_b32 v61, v246 offset:9648
	ds_read_b32 v62, v246 offset:9920
	ds_read_b32 v63, v246 offset:10192
	ds_read_b32 v64, v246 offset:10464
	ds_read_b32 v65, v246 offset:10736
	ds_read_b32 v74, v244 offset:4224
	ds_read_b32 v75, v244 offset:4356
	ds_read_b32 v76, v244 offset:4488
	ds_read_b32 v77, v244 offset:4620
	s_waitcnt lgkmcnt(0)
	v_mul_f32_e32 v26, v42, v26
	v_mul_f32_e32 v27, v43, v27
	v_mul_f32_e32 v28, v44, v28
	v_mul_f32_e32 v29, v45, v29
	v_mul_f32_e32 v30, v46, v30
	v_mul_f32_e32 v31, v47, v31
	v_mul_f32_e32 v32, v48, v32
	v_mul_f32_e32 v33, v49, v33
	v_mul_f32_e32 v66, v78, v66
	v_mul_f32_e32 v67, v78, v67
	v_mul_f32_e32 v68, v78, v68
	v_mul_f32_e32 v69, v78, v69
	s_nop 1
	v_mfma_f32_16x16x4_f32 v[66:69], v26, v34, v[66:69]
	v_mfma_f32_16x16x4_f32 v[66:69], v27, v35, v[66:69]
	v_mfma_f32_16x16x4_f32 v[66:69], v28, v36, v[66:69]
	v_mfma_f32_16x16x4_f32 v[66:69], v29, v37, v[66:69]
	v_mfma_f32_16x16x4_f32 v[66:69], v30, v38, v[66:69]
	v_mfma_f32_16x16x4_f32 v[66:69], v31, v39, v[66:69]
	v_mfma_f32_16x16x4_f32 v[66:69], v32, v40, v[66:69]
	v_mfma_f32_16x16x4_f32 v[66:69], v33, v41, v[66:69]
	v_mul_f32_e32 v50, v42, v50
	v_mul_f32_e32 v51, v43, v51
	v_mul_f32_e32 v52, v44, v52
	v_mul_f32_e32 v53, v45, v53
	v_mul_f32_e32 v54, v46, v54
	v_mul_f32_e32 v55, v47, v55
	v_mul_f32_e32 v56, v48, v56
	v_mul_f32_e32 v57, v49, v57
	v_mul_f32_e32 v70, v78, v70
	v_mul_f32_e32 v71, v78, v71
	v_mul_f32_e32 v72, v78, v72
	v_mul_f32_e32 v73, v78, v73
	s_nop 1
	v_mfma_f32_16x16x4_f32 v[70:73], v50, v34, v[70:73]
	v_mfma_f32_16x16x4_f32 v[70:73], v51, v35, v[70:73]
	v_mfma_f32_16x16x4_f32 v[70:73], v52, v36, v[70:73]
	v_mfma_f32_16x16x4_f32 v[70:73], v53, v37, v[70:73]
	v_mfma_f32_16x16x4_f32 v[70:73], v54, v38, v[70:73]
	v_mfma_f32_16x16x4_f32 v[70:73], v55, v39, v[70:73]
	v_mfma_f32_16x16x4_f32 v[70:73], v56, v40, v[70:73]
	v_mfma_f32_16x16x4_f32 v[70:73], v57, v41, v[70:73]
	v_mul_f32_e32 v58, v42, v58
	v_mul_f32_e32 v59, v43, v59
	v_mul_f32_e32 v60, v44, v60
	v_mul_f32_e32 v61, v45, v61
	v_mul_f32_e32 v62, v46, v62
	v_mul_f32_e32 v63, v47, v63
	v_mul_f32_e32 v64, v48, v64
	v_mul_f32_e32 v65, v49, v65
	v_mul_f32_e32 v74, v78, v74
	v_mul_f32_e32 v75, v78, v75
	v_mul_f32_e32 v76, v78, v76
	v_mul_f32_e32 v77, v78, v77
	s_nop 1
	v_mfma_f32_16x16x4_f32 v[74:77], v58, v34, v[74:77]
	v_mfma_f32_16x16x4_f32 v[74:77], v59, v35, v[74:77]
	v_mfma_f32_16x16x4_f32 v[74:77], v60, v36, v[74:77]
	v_mfma_f32_16x16x4_f32 v[74:77], v61, v37, v[74:77]
	v_mfma_f32_16x16x4_f32 v[74:77], v62, v38, v[74:77]
	v_mfma_f32_16x16x4_f32 v[74:77], v63, v39, v[74:77]
	v_mfma_f32_16x16x4_f32 v[74:77], v64, v40, v[74:77]
	v_mfma_f32_16x16x4_f32 v[74:77], v65, v41, v[74:77]
	s_nop 7
	s_nop 3
	ds_write_b32 v244, v66 offset:0
	ds_write_b32 v244, v67 offset:132
	ds_write_b32 v244, v68 offset:264
	ds_write_b32 v244, v69 offset:396
	ds_write_b32 v244, v70 offset:2112
	ds_write_b32 v244, v71 offset:2244
	ds_write_b32 v244, v72 offset:2376
	ds_write_b32 v244, v73 offset:2508
	ds_write_b32 v244, v74 offset:4224
	ds_write_b32 v244, v75 offset:4356
	ds_write_b32 v244, v76 offset:4488
	ds_write_b32 v244, v77 offset:4620
